# merge loop: ODIL loads issued with LSE loads; plus earlier ret_chunk/P0 edits; K-loop heads kept at baseline alignment
# speedup vs baseline: 1.0002x; 1.0002x over previous
.LBB0_452:
	v_ashrrev_i32_e32 v6, 6, v4
	v_ashrrev_i32_e32 v7, 31, v6
	v_bfe_u32 v10, v4, 3, 3
	v_lshlrev_b64 v[2:3], 5, v[6:7]
	v_lshl_add_u64 v[2:3], s[2:3], 0, v[2:3]
	v_lshlrev_b32_e32 v0, 2, v10
	v_lshl_add_u64 v[2:3], v[2:3], 0, v[0:1]
	v_add_co_u32_e32 v8, vcc, 0x100000, v2
	global_load_dword v0, v[2:3], off
	s_nop 0
	v_addc_co_u32_e32 v9, vcc, 0, v3, vcc
	global_load_dword v8, v[8:9], off
	v_add_co_u32_e32 v2, vcc, s10, v2
	v_lshlrev_b64 v[6:7], 9, v[6:7]
	s_nop 0
	v_addc_co_u32_e32 v3, vcc, 0, v3, vcc
	global_load_dword v9, v[2:3], off
	v_add_u32_e32 v4, s8, v4
	v_lshlrev_b32_e32 v184, 6, v10
	v_and_b32_e32 v185, 56, v5
	v_or3_b32 v6, v6, v184, v185
	v_lshlrev_b64 v[20:21], 1, v[6:7]
	v_lshl_add_u64 v[186:187], s[36:37], 0, v[20:21]
	global_load_dwordx4 v[188:191], v[186:187], off
	v_lshl_add_u64 v[186:187], s[38:39], 0, v[20:21]
	global_load_dwordx4 v[192:195], v[186:187], off
	v_lshl_add_u64 v[186:187], s[40:41], 0, v[20:21]
	global_load_dwordx4 v[196:199], v[186:187], off
	s_waitcnt vmcnt(3)
	v_max3_f32 v11, v0, v8, v9
	v_sub_f32_e32 v0, v0, v11
	v_cmp_gt_f32_e32 vcc, s97, v0
	s_nop 1
	v_cndmask_b32_e32 v2, 0, v233, vcc
	v_add_f32_e32 v0, v0, v2
	v_exp_f32_e32 v0, v0
	v_cndmask_b32_e32 v2, 0, v236, vcc
	v_ldexp_f32 v3, v0, v2
	v_sub_f32_e32 v0, v8, v11
	v_cmp_gt_f32_e32 vcc, s97, v0
	s_nop 1
	v_cndmask_b32_e32 v2, 0, v233, vcc
	v_add_f32_e32 v0, v0, v2
	v_exp_f32_e32 v0, v0
	v_cndmask_b32_e32 v2, 0, v236, vcc
	v_ldexp_f32 v2, v0, v2
	v_sub_f32_e32 v0, v9, v11
	v_cmp_gt_f32_e32 vcc, s97, v0
	s_nop 1
	v_cndmask_b32_e32 v8, 0, v233, vcc
	v_add_f32_e32 v0, v0, v8
	v_exp_f32_e32 v0, v0
	v_cndmask_b32_e32 v8, 0, v236, vcc
	v_ldexp_f32 v0, v0, v8
	v_add_f32_e32 v8, v3, v2
	v_add_f32_e32 v8, v0, v8
	v_div_scale_f32 v9, s[6:7], v8, v8, 1.0
	v_rcp_f32_e32 v11, v9
	s_mov_b32 s6, 0x1fffff
	v_fma_f32 v12, -v9, v11, 1.0
	v_fmac_f32_e32 v11, v12, v11
	v_div_scale_f32 v12, vcc, 1.0, v8, 1.0
	v_mul_f32_e32 v13, v12, v11
	v_fma_f32 v14, -v9, v13, v12
	v_fmac_f32_e32 v13, v14, v11
	v_fma_f32 v9, -v9, v13, v12
	v_div_fmas_f32 v9, v9, v11, v13
	v_div_fixup_f32 v18, v9, v8, 1.0
	v_pk_mul_f32 v[2:3], v[2:3], v[18:19] op_sel_hi:[1,0]
	v_mul_f32_e32 v0, v0, v18
	v_cmp_lt_i32_e32 vcc, s6, v4
	v_add_u32_e32 v5, s35, v5
	s_or_b64 s[62:63], vcc, s[62:63]
	s_waitcnt vmcnt(0)
	v_lshlrev_b32_e32 v22, 16, v188
	v_and_b32_e32 v19, 0xffff0000, v188
	v_and_b32_e32 v23, 0xffff0000, v192
	v_lshlrev_b32_e32 v18, 16, v192
	v_pk_mul_f32 v[22:23], v[2:3], v[22:23] op_sel:[1,0] op_sel_hi:[0,1]
	v_lshlrev_b32_e32 v24, 16, v196
	v_and_b32_e32 v25, 0xffff0000, v196
	v_pk_fma_f32 v[18:19], v[2:3], v[18:19], v[22:23]
	v_lshlrev_b32_e32 v10, 16, v189
	v_pk_fma_f32 v[18:19], v[0:1], v[24:25], v[18:19] op_sel_hi:[0,1,1]
	v_cvt_pk_bf16_f32 v6, v18, v19
	v_lshlrev_b32_e32 v18, 16, v193
	v_and_b32_e32 v11, 0xffff0000, v193
	v_and_b32_e32 v19, 0xffff0000, v189
	v_pk_mul_f32 v[10:11], v[2:3], v[10:11] op_sel:[1,0] op_sel_hi:[0,1]
	v_lshlrev_b32_e32 v14, 16, v197
	v_and_b32_e32 v15, 0xffff0000, v197
	v_pk_fma_f32 v[10:11], v[2:3], v[18:19], v[10:11]
	v_lshlrev_b32_e32 v18, 16, v198
	v_pk_fma_f32 v[10:11], v[0:1], v[14:15], v[10:11] op_sel_hi:[0,1,1]
	v_lshlrev_b32_e32 v14, 16, v190
	v_and_b32_e32 v15, 0xffff0000, v194
	v_cvt_pk_bf16_f32 v7, v10, v11
	v_lshlrev_b32_e32 v10, 16, v194
	v_and_b32_e32 v11, 0xffff0000, v190
	v_pk_mul_f32 v[14:15], v[2:3], v[14:15] op_sel:[1,0] op_sel_hi:[0,1]
	v_and_b32_e32 v19, 0xffff0000, v198
	v_pk_fma_f32 v[10:11], v[2:3], v[10:11], v[14:15]
	v_lshlrev_b32_e32 v12, 16, v191
	v_pk_fma_f32 v[10:11], v[0:1], v[18:19], v[10:11] op_sel_hi:[0,1,1]
	v_cvt_pk_bf16_f32 v8, v10, v11
	v_lshlrev_b32_e32 v10, 16, v195
	v_and_b32_e32 v13, 0xffff0000, v195
	v_and_b32_e32 v11, 0xffff0000, v191
	v_pk_mul_f32 v[12:13], v[2:3], v[12:13] op_sel:[1,0] op_sel_hi:[0,1]
	v_pk_fma_f32 v[2:3], v[2:3], v[10:11], v[12:13]
	v_lshlrev_b32_e32 v10, 16, v199
	v_and_b32_e32 v11, 0xffff0000, v199
	v_pk_fma_f32 v[2:3], v[0:1], v[10:11], v[2:3] op_sel_hi:[0,1,1]
	v_cvt_pk_bf16_f32 v9, v2, v3
	v_lshl_add_u64 v[2:3], s[46:47], 0, v[20:21]
	global_store_dwordx4 v[2:3], v[6:9], off
	s_andn2_b64 exec, exec, s[62:63]
	s_cbranch_execnz .LBB0_452
